# v88 stack + P1 GLU (u*sigmoid(g)) epilogue regenerated with packed v_pk_mul/v_pk_add for the plain steps, staged per 8-output block (same f32 arithmetic, symbolically proven)
# speedup vs baseline: 1.0014x; 1.0014x over previous
; __device__ __forceinline__ u32x4 pack8(f32x4 v0, f32x4 v1) { u32x4 w; w.x = cvt_pk_bf16(v0[0], v0[1]); w.y = cvt_pk_bf16(v0[2], v0[3]); w.z = cvt_pk_bf16(v1[0], v1[1]); w.w = cvt_pk_bf16(v1[2], v1[3]); return w; }
;     __device__ __forceinline__ void operator()(Acc& acc, const Unit& u, int wr, int wc, int fr, int fq, PG8_LAS unsigned char*) const {
;         if (u.c0 < 1024) {
;             bf16_t* base = O + (size_t)(u.r0 + wr * 64 + fr) * ldc + (u.c0 >> 1) + wc * 32 + 8 * fq;
; #pragma unroll
;             for (int ai = 0; ai < 2; ++ai)
; #pragma unroll
;                 for (int m = 0; m < 4; ++m) { f32x4 o[2];
; #pragma unroll
;                     for (int n = 0; n < 2; ++n) { const f32x4 uu = acc[ai][0][m][n], g = acc[ai][1][m][n]; f32x4 r;
; #pragma unroll
;                         for (int e = 0; e < 4; ++e) r[e] = uu[e] * __builtin_amdgcn_rcpf(1.f + __builtin_amdgcn_exp2f(-LOG2E * g[e]));
;                         o[n] = r; }
;                     *(u32x4*)(base + (size_t)(ai * HALF + m * 16) * ldc) = pack8(o[0], o[1]); }
.LBB0_109:
	v_mov_b32_e32 v200, 0xbfb8aa3b
	v_mov_b32_e32 v204, 1.0
	v_pk_mul_f32 v[120:121], v[120:121], v[200:201] op_sel_hi:[1,0]
	v_pk_mul_f32 v[122:123], v[122:123], v[200:201] op_sel_hi:[1,0]
	v_pk_mul_f32 v[112:113], v[112:113], v[200:201] op_sel_hi:[1,0]
	v_pk_mul_f32 v[114:115], v[114:115], v[200:201] op_sel_hi:[1,0]
	v_exp_f32_e32 v120, v120
	v_exp_f32_e32 v121, v121
	v_exp_f32_e32 v122, v122
	v_exp_f32_e32 v123, v123
	v_exp_f32_e32 v112, v112
	v_exp_f32_e32 v113, v113
	v_exp_f32_e32 v114, v114
	v_exp_f32_e32 v115, v115
	v_pk_add_f32 v[120:121], v[120:121], v[204:205] op_sel_hi:[1,0]
	v_pk_add_f32 v[122:123], v[122:123], v[204:205] op_sel_hi:[1,0]
	v_pk_add_f32 v[112:113], v[112:113], v[204:205] op_sel_hi:[1,0]
	v_pk_add_f32 v[114:115], v[114:115], v[204:205] op_sel_hi:[1,0]
	v_rcp_f32_e32 v120, v120
	v_rcp_f32_e32 v121, v121
	v_rcp_f32_e32 v122, v122
	v_rcp_f32_e32 v123, v123
	v_rcp_f32_e32 v112, v112
	v_rcp_f32_e32 v113, v113
	v_rcp_f32_e32 v114, v114
	v_rcp_f32_e32 v115, v115
	v_pk_mul_f32 v[124:125], v[124:125], v[120:121]
	v_pk_mul_f32 v[126:127], v[126:127], v[122:123]
	v_pk_mul_f32 v[116:117], v[116:117], v[112:113]
	v_pk_mul_f32 v[118:119], v[118:119], v[114:115]
	v_cvt_pk_bf16_f32 v112, v124, v125
	v_cvt_pk_bf16_f32 v113, v126, v127
	v_cvt_pk_bf16_f32 v114, v116, v117
	v_cvt_pk_bf16_f32 v115, v118, v119
	v_mov_b64_e32 v[150:151], s[10:11]
	v_mad_i64_i32 v[148:149], s[26:27], v149, s62, v[150:151]
	s_ashr_i32 s26, s6, 1
	s_ashr_i32 s27, s26, 31
	v_lshl_add_u64 v[148:149], s[26:27], 1, v[148:149]
	s_lshl_b32 s6, s57, 1
	v_lshl_add_u64 v[148:149], v[148:149], 0, s[6:7]
	v_lshl_add_u64 v[148:149], v[148:149], 0, v[136:137]
	flat_store_dwordx4 v[148:149], v[112:115]
	v_pk_mul_f32 v[104:105], v[104:105], v[200:201] op_sel_hi:[1,0]
	v_pk_mul_f32 v[106:107], v[106:107], v[200:201] op_sel_hi:[1,0]
	v_pk_mul_f32 v[96:97], v[96:97], v[200:201] op_sel_hi:[1,0]
	v_pk_mul_f32 v[98:99], v[98:99], v[200:201] op_sel_hi:[1,0]
	v_exp_f32_e32 v104, v104
	v_exp_f32_e32 v105, v105
	v_exp_f32_e32 v106, v106
	v_exp_f32_e32 v107, v107
	v_exp_f32_e32 v96, v96
	v_exp_f32_e32 v97, v97
	v_exp_f32_e32 v98, v98
	v_exp_f32_e32 v99, v99
	v_pk_add_f32 v[104:105], v[104:105], v[204:205] op_sel_hi:[1,0]
	v_pk_add_f32 v[106:107], v[106:107], v[204:205] op_sel_hi:[1,0]
	v_pk_add_f32 v[96:97], v[96:97], v[204:205] op_sel_hi:[1,0]
	v_pk_add_f32 v[98:99], v[98:99], v[204:205] op_sel_hi:[1,0]
	v_rcp_f32_e32 v104, v104
	v_rcp_f32_e32 v105, v105
	v_rcp_f32_e32 v106, v106
	v_rcp_f32_e32 v107, v107
	v_rcp_f32_e32 v96, v96
	v_rcp_f32_e32 v97, v97
	v_rcp_f32_e32 v98, v98
	v_rcp_f32_e32 v99, v99
	v_pk_mul_f32 v[108:109], v[108:109], v[104:105]
	v_pk_mul_f32 v[110:111], v[110:111], v[106:107]
	v_pk_mul_f32 v[100:101], v[100:101], v[96:97]
	v_pk_mul_f32 v[102:103], v[102:103], v[98:99]
	v_cvt_pk_bf16_f32 v96, v108, v109
	v_cvt_pk_bf16_f32 v97, v110, v111
	v_cvt_pk_bf16_f32 v98, v100, v101
	v_cvt_pk_bf16_f32 v99, v102, v103
	v_add_co_u32_e32 v100, vcc, s56, v148
	v_addc_co_u32_e32 v101, vcc, 0, v149, vcc
	flat_store_dwordx4 v[100:101], v[96:99]
	v_pk_mul_f32 v[88:89], v[88:89], v[200:201] op_sel_hi:[1,0]
	v_pk_mul_f32 v[90:91], v[90:91], v[200:201] op_sel_hi:[1,0]
	v_pk_mul_f32 v[80:81], v[80:81], v[200:201] op_sel_hi:[1,0]
	v_pk_mul_f32 v[82:83], v[82:83], v[200:201] op_sel_hi:[1,0]
	v_exp_f32_e32 v88, v88
	v_exp_f32_e32 v89, v89
	v_exp_f32_e32 v90, v90
	v_exp_f32_e32 v91, v91
	v_exp_f32_e32 v80, v80
	v_exp_f32_e32 v81, v81
	v_exp_f32_e32 v82, v82
	v_exp_f32_e32 v83, v83
	v_pk_add_f32 v[88:89], v[88:89], v[204:205] op_sel_hi:[1,0]
	v_pk_add_f32 v[90:91], v[90:91], v[204:205] op_sel_hi:[1,0]
	v_pk_add_f32 v[80:81], v[80:81], v[204:205] op_sel_hi:[1,0]
	v_pk_add_f32 v[82:83], v[82:83], v[204:205] op_sel_hi:[1,0]
	v_rcp_f32_e32 v88, v88
	v_rcp_f32_e32 v89, v89
	v_rcp_f32_e32 v90, v90
	v_rcp_f32_e32 v91, v91
	v_rcp_f32_e32 v80, v80
	v_rcp_f32_e32 v81, v81
	v_rcp_f32_e32 v82, v82
	v_rcp_f32_e32 v83, v83
	v_pk_mul_f32 v[92:93], v[92:93], v[88:89]
	v_pk_mul_f32 v[94:95], v[94:95], v[90:91]
	v_pk_mul_f32 v[84:85], v[84:85], v[80:81]
	v_pk_mul_f32 v[86:87], v[86:87], v[82:83]
	v_cvt_pk_bf16_f32 v80, v92, v93
	v_cvt_pk_bf16_f32 v81, v94, v95
	v_cvt_pk_bf16_f32 v82, v84, v85
	v_cvt_pk_bf16_f32 v83, v86, v87
	v_add_co_u32_e32 v84, vcc, s63, v148
	v_addc_co_u32_e32 v85, vcc, 0, v149, vcc
	flat_store_dwordx4 v[84:85], v[80:83]
	v_pk_mul_f32 v[72:73], v[72:73], v[200:201] op_sel_hi:[1,0]
	v_pk_mul_f32 v[74:75], v[74:75], v[200:201] op_sel_hi:[1,0]
	v_pk_mul_f32 v[64:65], v[64:65], v[200:201] op_sel_hi:[1,0]
	v_pk_mul_f32 v[66:67], v[66:67], v[200:201] op_sel_hi:[1,0]
	v_exp_f32_e32 v72, v72
	v_exp_f32_e32 v73, v73
	v_exp_f32_e32 v74, v74
	v_exp_f32_e32 v75, v75
	v_exp_f32_e32 v64, v64
	v_exp_f32_e32 v65, v65
	v_exp_f32_e32 v66, v66
	v_exp_f32_e32 v67, v67
	v_pk_add_f32 v[72:73], v[72:73], v[204:205] op_sel_hi:[1,0]
	v_pk_add_f32 v[74:75], v[74:75], v[204:205] op_sel_hi:[1,0]
	v_pk_add_f32 v[64:65], v[64:65], v[204:205] op_sel_hi:[1,0]
	v_pk_add_f32 v[66:67], v[66:67], v[204:205] op_sel_hi:[1,0]
	v_rcp_f32_e32 v72, v72
	v_rcp_f32_e32 v73, v73
	v_rcp_f32_e32 v74, v74
	v_rcp_f32_e32 v75, v75
	v_rcp_f32_e32 v64, v64
	v_rcp_f32_e32 v65, v65
	v_rcp_f32_e32 v66, v66
	v_rcp_f32_e32 v67, v67
	v_pk_mul_f32 v[76:77], v[76:77], v[72:73]
	v_pk_mul_f32 v[78:79], v[78:79], v[74:75]
	v_pk_mul_f32 v[68:69], v[68:69], v[64:65]
	v_pk_mul_f32 v[70:71], v[70:71], v[66:67]
	v_cvt_pk_bf16_f32 v64, v76, v77
; __device__ __forceinline__ u32x4 pack8(f32x4 v0, f32x4 v1) { u32x4 w; w.x = cvt_pk_bf16(v0[0], v0[1]); w.y = cvt_pk_bf16(v0[2], v0[3]); w.z = cvt_pk_bf16(v1[0], v1[1]); w.w = cvt_pk_bf16(v1[2], v1[3]); return w; }
;     __device__ __forceinline__ void operator()(Acc& acc, const Unit& u, int wr, int wc, int fr, int fq, PG8_LAS unsigned char*) const {
;         if (u.c0 < 1024) {
;             bf16_t* base = O + (size_t)(u.r0 + wr * 64 + fr) * ldc + (u.c0 >> 1) + wc * 32 + 8 * fq;
; #pragma unroll
;             for (int ai = 0; ai < 2; ++ai)
; #pragma unroll
;                 for (int m = 0; m < 4; ++m) { f32x4 o[2];
; #pragma unroll
;                     for (int n = 0; n < 2; ++n) { const f32x4 uu = acc[ai][0][m][n], g = acc[ai][1][m][n]; f32x4 r;
; #pragma unroll
;                         for (int e = 0; e < 4; ++e) r[e] = uu[e] * __builtin_amdgcn_rcpf(1.f + __builtin_amdgcn_exp2f(-LOG2E * g[e]));
;                         o[n] = r; }
;                     *(u32x4*)(base + (size_t)(ai * HALF + m * 16) * ldc) = pack8(o[0], o[1]); }
	v_cvt_pk_bf16_f32 v65, v78, v79
	v_cvt_pk_bf16_f32 v66, v68, v69
	v_cvt_pk_bf16_f32 v67, v70, v71
	v_add_co_u32_e32 v68, vcc, s64, v148
	v_addc_co_u32_e32 v69, vcc, 0, v149, vcc
	flat_store_dwordx4 v[68:69], v[64:67]
	v_pk_mul_f32 v[56:57], v[56:57], v[200:201] op_sel_hi:[1,0]
	v_pk_mul_f32 v[58:59], v[58:59], v[200:201] op_sel_hi:[1,0]
	v_pk_mul_f32 v[48:49], v[48:49], v[200:201] op_sel_hi:[1,0]
	v_pk_mul_f32 v[50:51], v[50:51], v[200:201] op_sel_hi:[1,0]
	v_exp_f32_e32 v56, v56
	v_exp_f32_e32 v57, v57
	v_exp_f32_e32 v58, v58
	v_exp_f32_e32 v59, v59
	v_exp_f32_e32 v48, v48
	v_exp_f32_e32 v49, v49
	v_exp_f32_e32 v50, v50
	v_exp_f32_e32 v51, v51
	v_pk_add_f32 v[56:57], v[56:57], v[204:205] op_sel_hi:[1,0]
	v_pk_add_f32 v[58:59], v[58:59], v[204:205] op_sel_hi:[1,0]
	v_pk_add_f32 v[48:49], v[48:49], v[204:205] op_sel_hi:[1,0]
	v_pk_add_f32 v[50:51], v[50:51], v[204:205] op_sel_hi:[1,0]
	v_rcp_f32_e32 v56, v56
	v_rcp_f32_e32 v57, v57
	v_rcp_f32_e32 v58, v58
	v_rcp_f32_e32 v59, v59
	v_rcp_f32_e32 v48, v48
	v_rcp_f32_e32 v49, v49
	v_rcp_f32_e32 v50, v50
	v_rcp_f32_e32 v51, v51
	v_pk_mul_f32 v[60:61], v[60:61], v[56:57]
	v_pk_mul_f32 v[62:63], v[62:63], v[58:59]
	v_pk_mul_f32 v[52:53], v[52:53], v[48:49]
	v_pk_mul_f32 v[54:55], v[54:55], v[50:51]
	v_cvt_pk_bf16_f32 v48, v60, v61
	v_cvt_pk_bf16_f32 v49, v62, v63
	v_cvt_pk_bf16_f32 v50, v52, v53
	v_cvt_pk_bf16_f32 v51, v54, v55
	v_add_co_u32_e32 v52, vcc, s65, v148
	v_addc_co_u32_e32 v53, vcc, 0, v149, vcc
	flat_store_dwordx4 v[52:53], v[48:51]
	v_pk_mul_f32 v[40:41], v[40:41], v[200:201] op_sel_hi:[1,0]
	v_pk_mul_f32 v[42:43], v[42:43], v[200:201] op_sel_hi:[1,0]
	v_pk_mul_f32 v[32:33], v[32:33], v[200:201] op_sel_hi:[1,0]
	v_pk_mul_f32 v[34:35], v[34:35], v[200:201] op_sel_hi:[1,0]
	v_exp_f32_e32 v40, v40
	v_exp_f32_e32 v41, v41
	v_exp_f32_e32 v42, v42
	v_exp_f32_e32 v43, v43
	v_exp_f32_e32 v32, v32
	v_exp_f32_e32 v33, v33
	v_exp_f32_e32 v34, v34
	v_exp_f32_e32 v35, v35
	v_pk_add_f32 v[40:41], v[40:41], v[204:205] op_sel_hi:[1,0]
	v_pk_add_f32 v[42:43], v[42:43], v[204:205] op_sel_hi:[1,0]
	v_pk_add_f32 v[32:33], v[32:33], v[204:205] op_sel_hi:[1,0]
	v_pk_add_f32 v[34:35], v[34:35], v[204:205] op_sel_hi:[1,0]
	v_rcp_f32_e32 v40, v40
	v_rcp_f32_e32 v41, v41
	v_rcp_f32_e32 v42, v42
	v_rcp_f32_e32 v43, v43
	v_rcp_f32_e32 v32, v32
	v_rcp_f32_e32 v33, v33
	v_rcp_f32_e32 v34, v34
	v_rcp_f32_e32 v35, v35
	v_pk_mul_f32 v[44:45], v[44:45], v[40:41]
	v_pk_mul_f32 v[46:47], v[46:47], v[42:43]
	v_pk_mul_f32 v[36:37], v[36:37], v[32:33]
	v_pk_mul_f32 v[38:39], v[38:39], v[34:35]
	v_cvt_pk_bf16_f32 v32, v44, v45
	v_cvt_pk_bf16_f32 v33, v46, v47
	v_cvt_pk_bf16_f32 v34, v36, v37
	v_cvt_pk_bf16_f32 v35, v38, v39
	v_add_co_u32_e32 v36, vcc, s66, v148
	v_addc_co_u32_e32 v37, vcc, 0, v149, vcc
	flat_store_dwordx4 v[36:37], v[32:35]
	v_pk_mul_f32 v[24:25], v[24:25], v[200:201] op_sel_hi:[1,0]
	v_pk_mul_f32 v[26:27], v[26:27], v[200:201] op_sel_hi:[1,0]
	v_pk_mul_f32 v[16:17], v[16:17], v[200:201] op_sel_hi:[1,0]
	v_pk_mul_f32 v[18:19], v[18:19], v[200:201] op_sel_hi:[1,0]
	v_exp_f32_e32 v24, v24
	v_exp_f32_e32 v25, v25
	v_exp_f32_e32 v26, v26
	v_exp_f32_e32 v27, v27
	v_exp_f32_e32 v16, v16
	v_exp_f32_e32 v17, v17
	v_exp_f32_e32 v18, v18
	v_exp_f32_e32 v19, v19
	v_pk_add_f32 v[24:25], v[24:25], v[204:205] op_sel_hi:[1,0]
	v_pk_add_f32 v[26:27], v[26:27], v[204:205] op_sel_hi:[1,0]
	v_pk_add_f32 v[16:17], v[16:17], v[204:205] op_sel_hi:[1,0]
	v_pk_add_f32 v[18:19], v[18:19], v[204:205] op_sel_hi:[1,0]
	v_rcp_f32_e32 v24, v24
	v_rcp_f32_e32 v25, v25
	v_rcp_f32_e32 v26, v26
	v_rcp_f32_e32 v27, v27
	v_rcp_f32_e32 v16, v16
	v_rcp_f32_e32 v17, v17
	v_rcp_f32_e32 v18, v18
	v_rcp_f32_e32 v19, v19
	v_pk_mul_f32 v[28:29], v[28:29], v[24:25]
	v_pk_mul_f32 v[30:31], v[30:31], v[26:27]
	v_pk_mul_f32 v[20:21], v[20:21], v[16:17]
	v_pk_mul_f32 v[22:23], v[22:23], v[18:19]
	v_cvt_pk_bf16_f32 v16, v28, v29
	v_cvt_pk_bf16_f32 v17, v30, v31
	v_cvt_pk_bf16_f32 v18, v20, v21
	v_cvt_pk_bf16_f32 v19, v22, v23
	v_add_co_u32_e32 v20, vcc, s67, v148
	s_nop 0
	v_addc_co_u32_e32 v21, vcc, 0, v149, vcc
	flat_store_dwordx4 v[20:21], v[16:19]
	v_pk_mul_f32 v[8:9], v[8:9], v[200:201] op_sel_hi:[1,0]
	v_pk_mul_f32 v[10:11], v[10:11], v[200:201] op_sel_hi:[1,0]
	v_pk_mul_f32 v[0:1], v[0:1], v[200:201] op_sel_hi:[1,0]
	v_pk_mul_f32 v[2:3], v[2:3], v[200:201] op_sel_hi:[1,0]
	v_exp_f32_e32 v8, v8
	v_exp_f32_e32 v9, v9
	v_exp_f32_e32 v10, v10
	v_exp_f32_e32 v11, v11
	v_exp_f32_e32 v0, v0
	v_exp_f32_e32 v1, v1
	v_exp_f32_e32 v2, v2
	v_exp_f32_e32 v3, v3
	v_pk_add_f32 v[8:9], v[8:9], v[204:205] op_sel_hi:[1,0]
	v_pk_add_f32 v[10:11], v[10:11], v[204:205] op_sel_hi:[1,0]
	v_pk_add_f32 v[0:1], v[0:1], v[204:205] op_sel_hi:[1,0]
	v_pk_add_f32 v[2:3], v[2:3], v[204:205] op_sel_hi:[1,0]
	v_rcp_f32_e32 v8, v8
	v_rcp_f32_e32 v9, v9
	v_rcp_f32_e32 v10, v10
	v_rcp_f32_e32 v11, v11
	v_rcp_f32_e32 v0, v0
	v_rcp_f32_e32 v1, v1
	v_rcp_f32_e32 v2, v2
	v_rcp_f32_e32 v3, v3
	v_pk_mul_f32 v[12:13], v[12:13], v[8:9]
	v_pk_mul_f32 v[14:15], v[14:15], v[10:11]
	v_pk_mul_f32 v[4:5], v[4:5], v[0:1]
	v_pk_mul_f32 v[6:7], v[6:7], v[2:3]
	v_cvt_pk_bf16_f32 v0, v12, v13
	v_cvt_pk_bf16_f32 v1, v14, v15
	v_cvt_pk_bf16_f32 v2, v4, v5
	v_cvt_pk_bf16_f32 v3, v6, v7
	v_add_co_u32_e32 v4, vcc, 0xdc000, v148
	s_nop 0
	v_addc_co_u32_e32 v5, vcc, 0, v149, vcc
	flat_store_dwordx4 v[4:5], v[0:3]
	s_andn2_b64 vcc, exec, s[4:5]
	s_mov_b64 s[4:5], -1
	s_cbranch_vccnz .LBB0_98
